# logf loop: also hoist the ss and b_forget loads of the epilogue to the top of the iteration
# speedup vs baseline: 1.0020x; 1.0011x over previous
; __device__ __forceinline__ float bflo(unsigned w) { return __uint_as_float(w << 16); }
; __device__ __forceinline__ float bfhi(unsigned w) { return __uint_as_float(w & 0xffff0000u); }
; __device__ __forceinline__ float rstd_of(u64 ss) { return rsqrtf((float)ss * (1.0f / 4294967296.0f) * (1.0f / DM) + EPS); }
; __device__ __forceinline__ void logf_phase(const Args& a, int l, const u64* ssv, LAS unsigned char* lds, int gw, int NGW, int wave, int lane) {
;     ...
;         const bf16_t* hp0 = hbp + (size_t)r0 * DM; const bf16_t* hp1 = hbp + (size_t)r1 * DM;
;         f32x4 h0[8], h1[8];
; #pragma unroll
;         for (int i = 0; i < 8; ++i) { const u32x2 w0 = *(const u32x2*)(hp0 + 4 * lane + 256 * i), w1 = *(const u32x2*)(hp1 + 4 * lane + 256 * i);
;             h0[i] = (f32x4){bflo(w0.x), bfhi(w0.x), bflo(w0.y), bfhi(w0.y)}; h1[i] = (f32x4){bflo(w1.x), bfhi(w1.x), bflo(w1.y), bfhi(w1.y)}; }
;         float sa[8], sb[8];
; #pragma unroll
;         for (int j = 0; j < 8; ++j) { float s0 = 0.f, s1 = 0.f;
; #pragma unroll
;             for (int i = 0; i < 8; ++i) { const f32x4 w = wl[j * (DM / 4) + lane + 64 * i];
;                 s0 += (h0[i][0] * w[0] + h0[i][1] * w[1]) + (h0[i][2] * w[2] + h0[i][3] * w[3]);
;                 s1 += (h1[i][0] * w[0] + h1[i][1] * w[1]) + (h1[i][2] * w[2] + h1[i][3] * w[3]); }
;             sa[j] = s0; sb[j] = s1;
;             __builtin_amdgcn_sched_barrier(0); }
;     ...
;         const int r = (lane & 8) ? r1 : r0; const float fsel = (lane & 8) ? f1 : f0;
;         const float xv = fsel * rstd_of(ssv[r]) + a.b_forget[l * 8 + (lane & 7)];
.LBB0_337:
	s_waitcnt lgkmcnt(0)
	ds_read_b128 v[140:143], v3
	ds_read_b128 v[144:147], v3 offset:8192
	ds_read_b128 v[148:151], v3 offset:16384
	ds_read_b128 v[152:155], v3 offset:24576
	ds_read_b128 v[156:159], v3 offset:32768
	ds_read_b128 v[160:163], v3 offset:40960
	ds_read_b128 v[164:167], v3 offset:49152
	ds_read_b128 v[168:171], v3 offset:57344
	v_mov_b32_e32 v176, s0
	v_add_u32_e32 v177, 1, v176
	v_cndmask_b32_e64 v176, v177, v176, s[42:43]
	v_mov_b32_e32 v177, 0
	v_lshl_add_u64 v[176:177], v[176:177], 3, s[4:5]
	global_load_dwordx2 v[176:177], v[176:177], off
	global_load_dword v178, v[4:5], off
	v_add_co_u32_e32 v10, vcc, 0x1000, v8
	global_load_dwordx2 v[100:101], v[8:9], off
	s_nop 0
	v_addc_co_u32_e32 v11, vcc, 0, v9, vcc
	global_load_dwordx2 v[116:117], v[10:11], off
	global_load_dwordx2 v[102:103], v[8:9], off offset:512
	global_load_dwordx2 v[118:119], v[10:11], off offset:512
	global_load_dwordx2 v[104:105], v[8:9], off offset:1024
	global_load_dwordx2 v[120:121], v[10:11], off offset:1024
	global_load_dwordx2 v[106:107], v[8:9], off offset:1536
	global_load_dwordx2 v[122:123], v[10:11], off offset:1536
	global_load_dwordx2 v[108:109], v[8:9], off offset:2048
	global_load_dwordx2 v[124:125], v[10:11], off offset:2048
	global_load_dwordx2 v[110:111], v[8:9], off offset:2560
	global_load_dwordx2 v[126:127], v[10:11], off offset:2560
	global_load_dwordx2 v[112:113], v[8:9], off offset:3072
	global_load_dwordx2 v[128:129], v[10:11], off offset:3072
	global_load_dwordx2 v[114:115], v[8:9], off offset:3584
	global_load_dwordx2 v[130:131], v[10:11], off offset:3584
	v_mov_b32_e32 v80, 0
	v_mov_b32_e32 v82, 0
	v_mov_b32_e32 v84, 0
	v_mov_b32_e32 v86, 0
	v_mov_b32_e32 v88, 0
	v_mov_b32_e32 v90, 0
	v_mov_b32_e32 v92, 0
	v_mov_b32_e32 v19, 0
	v_mov_b32_e32 v81, 0
	v_mov_b32_e32 v83, 0
	v_mov_b32_e32 v85, 0
	v_mov_b32_e32 v87, 0
	v_mov_b32_e32 v89, 0
	v_mov_b32_e32 v91, 0
	v_mov_b32_e32 v93, 0
	v_mov_b32_e32 v0, 0
	s_waitcnt vmcnt(14)
	v_lshlrev_b32_e32 v132, 16, v100
	v_and_b32_e32 v133, 0xffff0000, v100
	v_lshlrev_b32_e32 v134, 16, v101
	v_and_b32_e32 v135, 0xffff0000, v101
	v_lshlrev_b32_e32 v136, 16, v116
	v_and_b32_e32 v137, 0xffff0000, v116
	v_lshlrev_b32_e32 v138, 16, v117
	v_and_b32_e32 v139, 0xffff0000, v117
	s_waitcnt lgkmcnt(7)
	v_mul_f32_e32 v172, v141, v133
	v_mul_f32_e32 v174, v141, v137
	v_fmac_f32_e32 v172, v140, v132
	v_fmac_f32_e32 v174, v140, v136
	v_mul_f32_e32 v173, v143, v135
	v_mul_f32_e32 v175, v143, v139
	v_fmac_f32_e32 v173, v142, v134
	v_fmac_f32_e32 v175, v142, v138
	ds_read_b128 v[140:143], v3 offset:1024
	v_add_f32_e32 v172, v172, v173
	v_add_f32_e32 v174, v174, v175
	v_add_f32_e32 v80, v80, v172
	v_add_f32_e32 v81, v81, v174
	s_waitcnt lgkmcnt(7)
	v_mul_f32_e32 v172, v145, v133
	v_mul_f32_e32 v174, v145, v137
	v_fmac_f32_e32 v172, v144, v132
	v_fmac_f32_e32 v174, v144, v136
	v_mul_f32_e32 v173, v147, v135
	v_mul_f32_e32 v175, v147, v139
	v_fmac_f32_e32 v173, v146, v134
	v_fmac_f32_e32 v175, v146, v138
	ds_read_b128 v[144:147], v3 offset:9216
	v_add_f32_e32 v172, v172, v173
	v_add_f32_e32 v174, v174, v175
	v_add_f32_e32 v82, v82, v172
	v_add_f32_e32 v83, v83, v174
	s_waitcnt lgkmcnt(7)
	v_mul_f32_e32 v172, v149, v133
	v_mul_f32_e32 v174, v149, v137
	v_fmac_f32_e32 v172, v148, v132
	v_fmac_f32_e32 v174, v148, v136
	v_mul_f32_e32 v173, v151, v135
	v_mul_f32_e32 v175, v151, v139
	v_fmac_f32_e32 v173, v150, v134
	v_fmac_f32_e32 v175, v150, v138
	ds_read_b128 v[148:151], v3 offset:17408
	v_add_f32_e32 v172, v172, v173
	v_add_f32_e32 v174, v174, v175
	v_add_f32_e32 v84, v84, v172
	v_add_f32_e32 v85, v85, v174
	s_waitcnt lgkmcnt(7)
	v_mul_f32_e32 v172, v153, v133
	v_mul_f32_e32 v174, v153, v137
	v_fmac_f32_e32 v172, v152, v132
	v_fmac_f32_e32 v174, v152, v136
	v_mul_f32_e32 v173, v155, v135
	v_mul_f32_e32 v175, v155, v139
	v_fmac_f32_e32 v173, v154, v134
	v_fmac_f32_e32 v175, v154, v138
	ds_read_b128 v[152:155], v3 offset:25600
	v_add_f32_e32 v172, v172, v173
	v_add_f32_e32 v174, v174, v175
	v_add_f32_e32 v86, v86, v172
	v_add_f32_e32 v87, v87, v174
	s_waitcnt lgkmcnt(7)
	v_mul_f32_e32 v172, v157, v133
	v_mul_f32_e32 v174, v157, v137
	v_fmac_f32_e32 v172, v156, v132
	v_fmac_f32_e32 v174, v156, v136
	v_mul_f32_e32 v173, v159, v135
	v_mul_f32_e32 v175, v159, v139
	v_fmac_f32_e32 v173, v158, v134
	v_fmac_f32_e32 v175, v158, v138
	ds_read_b128 v[156:159], v3 offset:33792
	v_add_f32_e32 v172, v172, v173
	v_add_f32_e32 v174, v174, v175
	v_add_f32_e32 v88, v88, v172
	v_add_f32_e32 v89, v89, v174
	s_waitcnt lgkmcnt(7)
	v_mul_f32_e32 v172, v161, v133
	v_mul_f32_e32 v174, v161, v137
	v_fmac_f32_e32 v172, v160, v132
	v_fmac_f32_e32 v174, v160, v136
	v_mul_f32_e32 v173, v163, v135
	v_mul_f32_e32 v175, v163, v139
	v_fmac_f32_e32 v173, v162, v134
	v_fmac_f32_e32 v175, v162, v138
	ds_read_b128 v[160:163], v3 offset:41984
	v_add_f32_e32 v172, v172, v173
	v_add_f32_e32 v174, v174, v175
	v_add_f32_e32 v90, v90, v172
	v_add_f32_e32 v91, v91, v174
	s_waitcnt lgkmcnt(7)
	v_mul_f32_e32 v172, v165, v133
	v_mul_f32_e32 v174, v165, v137
	v_fmac_f32_e32 v172, v164, v132
	v_fmac_f32_e32 v174, v164, v136
	v_mul_f32_e32 v173, v167, v135
	v_mul_f32_e32 v175, v167, v139
	v_fmac_f32_e32 v173, v166, v134
	v_fmac_f32_e32 v175, v166, v138
	ds_read_b128 v[164:167], v3 offset:50176
	v_add_f32_e32 v172, v172, v173
	v_add_f32_e32 v174, v174, v175
	v_add_f32_e32 v92, v92, v172
	v_add_f32_e32 v93, v93, v174
	s_waitcnt lgkmcnt(7)
; __device__ __forceinline__ void logf_phase(const Args& a, int l, const u64* ssv, LAS unsigned char* lds, int gw, int NGW, int wave, int lane) {
;     ...
;         for (int j = 0; j < 8; ++j) { float s0 = 0.f, s1 = 0.f;
; #pragma unroll
;             for (int i = 0; i < 8; ++i) { const f32x4 w = wl[j * (DM / 4) + lane + 64 * i];
;                 s0 += (h0[i][0] * w[0] + h0[i][1] * w[1]) + (h0[i][2] * w[2] + h0[i][3] * w[3]);
;                 s1 += (h1[i][0] * w[0] + h1[i][1] * w[1]) + (h1[i][2] * w[2] + h1[i][3] * w[3]); }
;             sa[j] = s0; sb[j] = s1;
;             __builtin_amdgcn_sched_barrier(0); }
	v_mul_f32_e32 v172, v169, v133
	v_mul_f32_e32 v174, v169, v137
	v_fmac_f32_e32 v172, v168, v132
	v_fmac_f32_e32 v174, v168, v136
	v_mul_f32_e32 v173, v171, v135
	v_mul_f32_e32 v175, v171, v139
	v_fmac_f32_e32 v173, v170, v134
	v_fmac_f32_e32 v175, v170, v138
	ds_read_b128 v[168:171], v3 offset:58368
	v_add_f32_e32 v172, v172, v173
	v_add_f32_e32 v174, v174, v175
	v_add_f32_e32 v19, v19, v172
	v_add_f32_e32 v0, v0, v174
	s_waitcnt vmcnt(12)
	v_lshlrev_b32_e32 v132, 16, v102
	v_and_b32_e32 v133, 0xffff0000, v102
	v_lshlrev_b32_e32 v134, 16, v103
	v_and_b32_e32 v135, 0xffff0000, v103
	v_lshlrev_b32_e32 v136, 16, v118
	v_and_b32_e32 v137, 0xffff0000, v118
	v_lshlrev_b32_e32 v138, 16, v119
	v_and_b32_e32 v139, 0xffff0000, v119
	s_waitcnt lgkmcnt(7)
	v_mul_f32_e32 v172, v141, v133
	v_mul_f32_e32 v174, v141, v137
	v_fmac_f32_e32 v172, v140, v132
	v_fmac_f32_e32 v174, v140, v136
	v_mul_f32_e32 v173, v143, v135
	v_mul_f32_e32 v175, v143, v139
	v_fmac_f32_e32 v173, v142, v134
	v_fmac_f32_e32 v175, v142, v138
	ds_read_b128 v[140:143], v3 offset:2048
	v_add_f32_e32 v172, v172, v173
	v_add_f32_e32 v174, v174, v175
	v_add_f32_e32 v80, v80, v172
	v_add_f32_e32 v81, v81, v174
	s_waitcnt lgkmcnt(7)
	v_mul_f32_e32 v172, v145, v133
	v_mul_f32_e32 v174, v145, v137
	v_fmac_f32_e32 v172, v144, v132
	v_fmac_f32_e32 v174, v144, v136
	v_mul_f32_e32 v173, v147, v135
	v_mul_f32_e32 v175, v147, v139
	v_fmac_f32_e32 v173, v146, v134
	v_fmac_f32_e32 v175, v146, v138
	ds_read_b128 v[144:147], v3 offset:10240
	v_add_f32_e32 v172, v172, v173
	v_add_f32_e32 v174, v174, v175
	v_add_f32_e32 v82, v82, v172
	v_add_f32_e32 v83, v83, v174
	s_waitcnt lgkmcnt(7)
	v_mul_f32_e32 v172, v149, v133
	v_mul_f32_e32 v174, v149, v137
	v_fmac_f32_e32 v172, v148, v132
	v_fmac_f32_e32 v174, v148, v136
	v_mul_f32_e32 v173, v151, v135
	v_mul_f32_e32 v175, v151, v139
	v_fmac_f32_e32 v173, v150, v134
	v_fmac_f32_e32 v175, v150, v138
	ds_read_b128 v[148:151], v3 offset:18432
	v_add_f32_e32 v172, v172, v173
	v_add_f32_e32 v174, v174, v175
	v_add_f32_e32 v84, v84, v172
	v_add_f32_e32 v85, v85, v174
	s_waitcnt lgkmcnt(7)
	v_mul_f32_e32 v172, v153, v133
	v_mul_f32_e32 v174, v153, v137
	v_fmac_f32_e32 v172, v152, v132
	v_fmac_f32_e32 v174, v152, v136
	v_mul_f32_e32 v173, v155, v135
	v_mul_f32_e32 v175, v155, v139
	v_fmac_f32_e32 v173, v154, v134
	v_fmac_f32_e32 v175, v154, v138
	ds_read_b128 v[152:155], v3 offset:26624
	v_add_f32_e32 v172, v172, v173
	v_add_f32_e32 v174, v174, v175
	v_add_f32_e32 v86, v86, v172
	v_add_f32_e32 v87, v87, v174
	s_waitcnt lgkmcnt(7)
	v_mul_f32_e32 v172, v157, v133
	v_mul_f32_e32 v174, v157, v137
	v_fmac_f32_e32 v172, v156, v132
	v_fmac_f32_e32 v174, v156, v136
	v_mul_f32_e32 v173, v159, v135
	v_mul_f32_e32 v175, v159, v139
	v_fmac_f32_e32 v173, v158, v134
	v_fmac_f32_e32 v175, v158, v138
	ds_read_b128 v[156:159], v3 offset:34816
	v_add_f32_e32 v172, v172, v173
	v_add_f32_e32 v174, v174, v175
	v_add_f32_e32 v88, v88, v172
	v_add_f32_e32 v89, v89, v174
	s_waitcnt lgkmcnt(7)
	v_mul_f32_e32 v172, v161, v133
	v_mul_f32_e32 v174, v161, v137
	v_fmac_f32_e32 v172, v160, v132
	v_fmac_f32_e32 v174, v160, v136
	v_mul_f32_e32 v173, v163, v135
	v_mul_f32_e32 v175, v163, v139
	v_fmac_f32_e32 v173, v162, v134
	v_fmac_f32_e32 v175, v162, v138
	ds_read_b128 v[160:163], v3 offset:43008
	v_add_f32_e32 v172, v172, v173
	v_add_f32_e32 v174, v174, v175
	v_add_f32_e32 v90, v90, v172
	v_add_f32_e32 v91, v91, v174
	s_waitcnt lgkmcnt(7)
	v_mul_f32_e32 v172, v165, v133
	v_mul_f32_e32 v174, v165, v137
	v_fmac_f32_e32 v172, v164, v132
	v_fmac_f32_e32 v174, v164, v136
	v_mul_f32_e32 v173, v167, v135
	v_mul_f32_e32 v175, v167, v139
	v_fmac_f32_e32 v173, v166, v134
	v_fmac_f32_e32 v175, v166, v138
	ds_read_b128 v[164:167], v3 offset:51200
	v_add_f32_e32 v172, v172, v173
	v_add_f32_e32 v174, v174, v175
	v_add_f32_e32 v92, v92, v172
	v_add_f32_e32 v93, v93, v174
	s_waitcnt lgkmcnt(7)
	v_mul_f32_e32 v172, v169, v133
	v_mul_f32_e32 v174, v169, v137
	v_fmac_f32_e32 v172, v168, v132
	v_fmac_f32_e32 v174, v168, v136
	v_mul_f32_e32 v173, v171, v135
	v_mul_f32_e32 v175, v171, v139
	v_fmac_f32_e32 v173, v170, v134
	v_fmac_f32_e32 v175, v170, v138
	ds_read_b128 v[168:171], v3 offset:59392
	v_add_f32_e32 v172, v172, v173
	v_add_f32_e32 v174, v174, v175
	v_add_f32_e32 v19, v19, v172
	v_add_f32_e32 v0, v0, v174
	s_waitcnt vmcnt(10)
	v_lshlrev_b32_e32 v132, 16, v104
	v_and_b32_e32 v133, 0xffff0000, v104
	v_lshlrev_b32_e32 v134, 16, v105
	v_and_b32_e32 v135, 0xffff0000, v105
	v_lshlrev_b32_e32 v136, 16, v120
	v_and_b32_e32 v137, 0xffff0000, v120
	v_lshlrev_b32_e32 v138, 16, v121
	v_and_b32_e32 v139, 0xffff0000, v121
	s_waitcnt lgkmcnt(7)
	v_mul_f32_e32 v172, v141, v133
	v_mul_f32_e32 v174, v141, v137
	v_fmac_f32_e32 v172, v140, v132
	v_fmac_f32_e32 v174, v140, v136
	v_mul_f32_e32 v173, v143, v135
	v_mul_f32_e32 v175, v143, v139
	v_fmac_f32_e32 v173, v142, v134
	v_fmac_f32_e32 v175, v142, v138
	ds_read_b128 v[140:143], v3 offset:3072
	v_add_f32_e32 v172, v172, v173
	v_add_f32_e32 v174, v174, v175
	v_add_f32_e32 v80, v80, v172
	v_add_f32_e32 v81, v81, v174
	s_waitcnt lgkmcnt(7)
	v_mul_f32_e32 v172, v145, v133
	v_mul_f32_e32 v174, v145, v137
	v_fmac_f32_e32 v172, v144, v132
	v_fmac_f32_e32 v174, v144, v136
	v_mul_f32_e32 v173, v147, v135
	v_mul_f32_e32 v175, v147, v139
	v_fmac_f32_e32 v173, v146, v134
	v_fmac_f32_e32 v175, v146, v138
	ds_read_b128 v[144:147], v3 offset:11264
	v_add_f32_e32 v172, v172, v173
	v_add_f32_e32 v174, v174, v175
	v_add_f32_e32 v82, v82, v172
	v_add_f32_e32 v83, v83, v174
	s_waitcnt lgkmcnt(7)
; __device__ __forceinline__ void logf_phase(const Args& a, int l, const u64* ssv, LAS unsigned char* lds, int gw, int NGW, int wave, int lane) {
;     ...
;         for (int j = 0; j < 8; ++j) { float s0 = 0.f, s1 = 0.f;
; #pragma unroll
;             for (int i = 0; i < 8; ++i) { const f32x4 w = wl[j * (DM / 4) + lane + 64 * i];
;                 s0 += (h0[i][0] * w[0] + h0[i][1] * w[1]) + (h0[i][2] * w[2] + h0[i][3] * w[3]);
;                 s1 += (h1[i][0] * w[0] + h1[i][1] * w[1]) + (h1[i][2] * w[2] + h1[i][3] * w[3]); }
;             sa[j] = s0; sb[j] = s1;
;             __builtin_amdgcn_sched_barrier(0); }
	v_mul_f32_e32 v172, v149, v133
	v_mul_f32_e32 v174, v149, v137
	v_fmac_f32_e32 v172, v148, v132
	v_fmac_f32_e32 v174, v148, v136
	v_mul_f32_e32 v173, v151, v135
	v_mul_f32_e32 v175, v151, v139
	v_fmac_f32_e32 v173, v150, v134
	v_fmac_f32_e32 v175, v150, v138
	ds_read_b128 v[148:151], v3 offset:19456
	v_add_f32_e32 v172, v172, v173
	v_add_f32_e32 v174, v174, v175
	v_add_f32_e32 v84, v84, v172
	v_add_f32_e32 v85, v85, v174
	s_waitcnt lgkmcnt(7)
	v_mul_f32_e32 v172, v153, v133
	v_mul_f32_e32 v174, v153, v137
	v_fmac_f32_e32 v172, v152, v132
	v_fmac_f32_e32 v174, v152, v136
	v_mul_f32_e32 v173, v155, v135
	v_mul_f32_e32 v175, v155, v139
	v_fmac_f32_e32 v173, v154, v134
	v_fmac_f32_e32 v175, v154, v138
	ds_read_b128 v[152:155], v3 offset:27648
	v_add_f32_e32 v172, v172, v173
	v_add_f32_e32 v174, v174, v175
	v_add_f32_e32 v86, v86, v172
	v_add_f32_e32 v87, v87, v174
	s_waitcnt lgkmcnt(7)
	v_mul_f32_e32 v172, v157, v133
	v_mul_f32_e32 v174, v157, v137
	v_fmac_f32_e32 v172, v156, v132
	v_fmac_f32_e32 v174, v156, v136
	v_mul_f32_e32 v173, v159, v135
	v_mul_f32_e32 v175, v159, v139
	v_fmac_f32_e32 v173, v158, v134
	v_fmac_f32_e32 v175, v158, v138
	ds_read_b128 v[156:159], v3 offset:35840
	v_add_f32_e32 v172, v172, v173
	v_add_f32_e32 v174, v174, v175
	v_add_f32_e32 v88, v88, v172
	v_add_f32_e32 v89, v89, v174
	s_waitcnt lgkmcnt(7)
	v_mul_f32_e32 v172, v161, v133
	v_mul_f32_e32 v174, v161, v137
	v_fmac_f32_e32 v172, v160, v132
	v_fmac_f32_e32 v174, v160, v136
	v_mul_f32_e32 v173, v163, v135
	v_mul_f32_e32 v175, v163, v139
	v_fmac_f32_e32 v173, v162, v134
	v_fmac_f32_e32 v175, v162, v138
	ds_read_b128 v[160:163], v3 offset:44032
	v_add_f32_e32 v172, v172, v173
	v_add_f32_e32 v174, v174, v175
	v_add_f32_e32 v90, v90, v172
	v_add_f32_e32 v91, v91, v174
	s_waitcnt lgkmcnt(7)
	v_mul_f32_e32 v172, v165, v133
	v_mul_f32_e32 v174, v165, v137
	v_fmac_f32_e32 v172, v164, v132
	v_fmac_f32_e32 v174, v164, v136
	v_mul_f32_e32 v173, v167, v135
	v_mul_f32_e32 v175, v167, v139
	v_fmac_f32_e32 v173, v166, v134
	v_fmac_f32_e32 v175, v166, v138
	ds_read_b128 v[164:167], v3 offset:52224
	v_add_f32_e32 v172, v172, v173
	v_add_f32_e32 v174, v174, v175
	v_add_f32_e32 v92, v92, v172
	v_add_f32_e32 v93, v93, v174
	s_waitcnt lgkmcnt(7)
	v_mul_f32_e32 v172, v169, v133
	v_mul_f32_e32 v174, v169, v137
	v_fmac_f32_e32 v172, v168, v132
	v_fmac_f32_e32 v174, v168, v136
	v_mul_f32_e32 v173, v171, v135
	v_mul_f32_e32 v175, v171, v139
	v_fmac_f32_e32 v173, v170, v134
	v_fmac_f32_e32 v175, v170, v138
	ds_read_b128 v[168:171], v3 offset:60416
	v_add_f32_e32 v172, v172, v173
	v_add_f32_e32 v174, v174, v175
	v_add_f32_e32 v19, v19, v172
	v_add_f32_e32 v0, v0, v174
	s_waitcnt vmcnt(8)
	v_lshlrev_b32_e32 v132, 16, v106
	v_and_b32_e32 v133, 0xffff0000, v106
	v_lshlrev_b32_e32 v134, 16, v107
	v_and_b32_e32 v135, 0xffff0000, v107
	v_lshlrev_b32_e32 v136, 16, v122
	v_and_b32_e32 v137, 0xffff0000, v122
	v_lshlrev_b32_e32 v138, 16, v123
	v_and_b32_e32 v139, 0xffff0000, v123
	s_waitcnt lgkmcnt(7)
	v_mul_f32_e32 v172, v141, v133
	v_mul_f32_e32 v174, v141, v137
	v_fmac_f32_e32 v172, v140, v132
	v_fmac_f32_e32 v174, v140, v136
	v_mul_f32_e32 v173, v143, v135
	v_mul_f32_e32 v175, v143, v139
	v_fmac_f32_e32 v173, v142, v134
	v_fmac_f32_e32 v175, v142, v138
	ds_read_b128 v[140:143], v3 offset:4096
	v_add_f32_e32 v172, v172, v173
	v_add_f32_e32 v174, v174, v175
	v_add_f32_e32 v80, v80, v172
	v_add_f32_e32 v81, v81, v174
	s_waitcnt lgkmcnt(7)
	v_mul_f32_e32 v172, v145, v133
	v_mul_f32_e32 v174, v145, v137
	v_fmac_f32_e32 v172, v144, v132
	v_fmac_f32_e32 v174, v144, v136
	v_mul_f32_e32 v173, v147, v135
	v_mul_f32_e32 v175, v147, v139
	v_fmac_f32_e32 v173, v146, v134
	v_fmac_f32_e32 v175, v146, v138
	ds_read_b128 v[144:147], v3 offset:12288
	v_add_f32_e32 v172, v172, v173
	v_add_f32_e32 v174, v174, v175
	v_add_f32_e32 v82, v82, v172
	v_add_f32_e32 v83, v83, v174
	s_waitcnt lgkmcnt(7)
	v_mul_f32_e32 v172, v149, v133
	v_mul_f32_e32 v174, v149, v137
	v_fmac_f32_e32 v172, v148, v132
	v_fmac_f32_e32 v174, v148, v136
	v_mul_f32_e32 v173, v151, v135
	v_mul_f32_e32 v175, v151, v139
	v_fmac_f32_e32 v173, v150, v134
	v_fmac_f32_e32 v175, v150, v138
	ds_read_b128 v[148:151], v3 offset:20480
	v_add_f32_e32 v172, v172, v173
	v_add_f32_e32 v174, v174, v175
	v_add_f32_e32 v84, v84, v172
	v_add_f32_e32 v85, v85, v174
	s_waitcnt lgkmcnt(7)
	v_mul_f32_e32 v172, v153, v133
	v_mul_f32_e32 v174, v153, v137
	v_fmac_f32_e32 v172, v152, v132
	v_fmac_f32_e32 v174, v152, v136
	v_mul_f32_e32 v173, v155, v135
	v_mul_f32_e32 v175, v155, v139
	v_fmac_f32_e32 v173, v154, v134
	v_fmac_f32_e32 v175, v154, v138
	ds_read_b128 v[152:155], v3 offset:28672
	v_add_f32_e32 v172, v172, v173
	v_add_f32_e32 v174, v174, v175
	v_add_f32_e32 v86, v86, v172
	v_add_f32_e32 v87, v87, v174
	s_waitcnt lgkmcnt(7)
	v_mul_f32_e32 v172, v157, v133
	v_mul_f32_e32 v174, v157, v137
	v_fmac_f32_e32 v172, v156, v132
	v_fmac_f32_e32 v174, v156, v136
	v_mul_f32_e32 v173, v159, v135
	v_mul_f32_e32 v175, v159, v139
	v_fmac_f32_e32 v173, v158, v134
	v_fmac_f32_e32 v175, v158, v138
	ds_read_b128 v[156:159], v3 offset:36864
	v_add_f32_e32 v172, v172, v173
	v_add_f32_e32 v174, v174, v175
	v_add_f32_e32 v88, v88, v172
	v_add_f32_e32 v89, v89, v174
	s_waitcnt lgkmcnt(7)
	v_mul_f32_e32 v172, v161, v133
	v_mul_f32_e32 v174, v161, v137
	v_fmac_f32_e32 v172, v160, v132
	v_fmac_f32_e32 v174, v160, v136
	v_mul_f32_e32 v173, v163, v135
	v_mul_f32_e32 v175, v163, v139
	v_fmac_f32_e32 v173, v162, v134
	v_fmac_f32_e32 v175, v162, v138
	ds_read_b128 v[160:163], v3 offset:45056
	v_add_f32_e32 v172, v172, v173
	v_add_f32_e32 v174, v174, v175
	v_add_f32_e32 v90, v90, v172
	v_add_f32_e32 v91, v91, v174
	s_waitcnt lgkmcnt(7)
; __device__ __forceinline__ void logf_phase(const Args& a, int l, const u64* ssv, LAS unsigned char* lds, int gw, int NGW, int wave, int lane) {
;     ...
;         for (int j = 0; j < 8; ++j) { float s0 = 0.f, s1 = 0.f;
; #pragma unroll
;             for (int i = 0; i < 8; ++i) { const f32x4 w = wl[j * (DM / 4) + lane + 64 * i];
;                 s0 += (h0[i][0] * w[0] + h0[i][1] * w[1]) + (h0[i][2] * w[2] + h0[i][3] * w[3]);
;                 s1 += (h1[i][0] * w[0] + h1[i][1] * w[1]) + (h1[i][2] * w[2] + h1[i][3] * w[3]); }
;             sa[j] = s0; sb[j] = s1;
;             __builtin_amdgcn_sched_barrier(0); }
	v_mul_f32_e32 v172, v165, v133
	v_mul_f32_e32 v174, v165, v137
	v_fmac_f32_e32 v172, v164, v132
	v_fmac_f32_e32 v174, v164, v136
	v_mul_f32_e32 v173, v167, v135
	v_mul_f32_e32 v175, v167, v139
	v_fmac_f32_e32 v173, v166, v134
	v_fmac_f32_e32 v175, v166, v138
	ds_read_b128 v[164:167], v3 offset:53248
	v_add_f32_e32 v172, v172, v173
	v_add_f32_e32 v174, v174, v175
	v_add_f32_e32 v92, v92, v172
	v_add_f32_e32 v93, v93, v174
	s_waitcnt lgkmcnt(7)
	v_mul_f32_e32 v172, v169, v133
	v_mul_f32_e32 v174, v169, v137
	v_fmac_f32_e32 v172, v168, v132
	v_fmac_f32_e32 v174, v168, v136
	v_mul_f32_e32 v173, v171, v135
	v_mul_f32_e32 v175, v171, v139
	v_fmac_f32_e32 v173, v170, v134
	v_fmac_f32_e32 v175, v170, v138
	ds_read_b128 v[168:171], v3 offset:61440
	v_add_f32_e32 v172, v172, v173
	v_add_f32_e32 v174, v174, v175
	v_add_f32_e32 v19, v19, v172
	v_add_f32_e32 v0, v0, v174
	s_waitcnt vmcnt(6)
	v_lshlrev_b32_e32 v132, 16, v108
	v_and_b32_e32 v133, 0xffff0000, v108
	v_lshlrev_b32_e32 v134, 16, v109
	v_and_b32_e32 v135, 0xffff0000, v109
	v_lshlrev_b32_e32 v136, 16, v124
	v_and_b32_e32 v137, 0xffff0000, v124
	v_lshlrev_b32_e32 v138, 16, v125
	v_and_b32_e32 v139, 0xffff0000, v125
	s_waitcnt lgkmcnt(7)
	v_mul_f32_e32 v172, v141, v133
	v_mul_f32_e32 v174, v141, v137
	v_fmac_f32_e32 v172, v140, v132
	v_fmac_f32_e32 v174, v140, v136
	v_mul_f32_e32 v173, v143, v135
	v_mul_f32_e32 v175, v143, v139
	v_fmac_f32_e32 v173, v142, v134
	v_fmac_f32_e32 v175, v142, v138
	ds_read_b128 v[140:143], v3 offset:5120
	v_add_f32_e32 v172, v172, v173
	v_add_f32_e32 v174, v174, v175
	v_add_f32_e32 v80, v80, v172
	v_add_f32_e32 v81, v81, v174
	s_waitcnt lgkmcnt(7)
	v_mul_f32_e32 v172, v145, v133
	v_mul_f32_e32 v174, v145, v137
	v_fmac_f32_e32 v172, v144, v132
	v_fmac_f32_e32 v174, v144, v136
	v_mul_f32_e32 v173, v147, v135
	v_mul_f32_e32 v175, v147, v139
	v_fmac_f32_e32 v173, v146, v134
	v_fmac_f32_e32 v175, v146, v138
	ds_read_b128 v[144:147], v3 offset:13312
	v_add_f32_e32 v172, v172, v173
	v_add_f32_e32 v174, v174, v175
	v_add_f32_e32 v82, v82, v172
	v_add_f32_e32 v83, v83, v174
	s_waitcnt lgkmcnt(7)
	v_mul_f32_e32 v172, v149, v133
	v_mul_f32_e32 v174, v149, v137
	v_fmac_f32_e32 v172, v148, v132
	v_fmac_f32_e32 v174, v148, v136
	v_mul_f32_e32 v173, v151, v135
	v_mul_f32_e32 v175, v151, v139
	v_fmac_f32_e32 v173, v150, v134
	v_fmac_f32_e32 v175, v150, v138
	ds_read_b128 v[148:151], v3 offset:21504
	v_add_f32_e32 v172, v172, v173
	v_add_f32_e32 v174, v174, v175
	v_add_f32_e32 v84, v84, v172
	v_add_f32_e32 v85, v85, v174
	s_waitcnt lgkmcnt(7)
	v_mul_f32_e32 v172, v153, v133
	v_mul_f32_e32 v174, v153, v137
	v_fmac_f32_e32 v172, v152, v132
	v_fmac_f32_e32 v174, v152, v136
	v_mul_f32_e32 v173, v155, v135
	v_mul_f32_e32 v175, v155, v139
	v_fmac_f32_e32 v173, v154, v134
	v_fmac_f32_e32 v175, v154, v138
	ds_read_b128 v[152:155], v3 offset:29696
	v_add_f32_e32 v172, v172, v173
	v_add_f32_e32 v174, v174, v175
	v_add_f32_e32 v86, v86, v172
	v_add_f32_e32 v87, v87, v174
	s_waitcnt lgkmcnt(7)
	v_mul_f32_e32 v172, v157, v133
	v_mul_f32_e32 v174, v157, v137
	v_fmac_f32_e32 v172, v156, v132
	v_fmac_f32_e32 v174, v156, v136
	v_mul_f32_e32 v173, v159, v135
	v_mul_f32_e32 v175, v159, v139
	v_fmac_f32_e32 v173, v158, v134
	v_fmac_f32_e32 v175, v158, v138
	ds_read_b128 v[156:159], v3 offset:37888
	v_add_f32_e32 v172, v172, v173
	v_add_f32_e32 v174, v174, v175
	v_add_f32_e32 v88, v88, v172
	v_add_f32_e32 v89, v89, v174
	s_waitcnt lgkmcnt(7)
	v_mul_f32_e32 v172, v161, v133
	v_mul_f32_e32 v174, v161, v137
	v_fmac_f32_e32 v172, v160, v132
	v_fmac_f32_e32 v174, v160, v136
	v_mul_f32_e32 v173, v163, v135
	v_mul_f32_e32 v175, v163, v139
	v_fmac_f32_e32 v173, v162, v134
	v_fmac_f32_e32 v175, v162, v138
	ds_read_b128 v[160:163], v3 offset:46080
	v_add_f32_e32 v172, v172, v173
	v_add_f32_e32 v174, v174, v175
	v_add_f32_e32 v90, v90, v172
	v_add_f32_e32 v91, v91, v174
	s_waitcnt lgkmcnt(7)
	v_mul_f32_e32 v172, v165, v133
	v_mul_f32_e32 v174, v165, v137
	v_fmac_f32_e32 v172, v164, v132
	v_fmac_f32_e32 v174, v164, v136
	v_mul_f32_e32 v173, v167, v135
	v_mul_f32_e32 v175, v167, v139
	v_fmac_f32_e32 v173, v166, v134
	v_fmac_f32_e32 v175, v166, v138
	ds_read_b128 v[164:167], v3 offset:54272
	v_add_f32_e32 v172, v172, v173
	v_add_f32_e32 v174, v174, v175
	v_add_f32_e32 v92, v92, v172
	v_add_f32_e32 v93, v93, v174
	s_waitcnt lgkmcnt(7)
	v_mul_f32_e32 v172, v169, v133
	v_mul_f32_e32 v174, v169, v137
	v_fmac_f32_e32 v172, v168, v132
	v_fmac_f32_e32 v174, v168, v136
	v_mul_f32_e32 v173, v171, v135
	v_mul_f32_e32 v175, v171, v139
	v_fmac_f32_e32 v173, v170, v134
	v_fmac_f32_e32 v175, v170, v138
	ds_read_b128 v[168:171], v3 offset:62464
	v_add_f32_e32 v172, v172, v173
	v_add_f32_e32 v174, v174, v175
	v_add_f32_e32 v19, v19, v172
	v_add_f32_e32 v0, v0, v174
	s_waitcnt vmcnt(4)
	v_lshlrev_b32_e32 v132, 16, v110
	v_and_b32_e32 v133, 0xffff0000, v110
	v_lshlrev_b32_e32 v134, 16, v111
	v_and_b32_e32 v135, 0xffff0000, v111
	v_lshlrev_b32_e32 v136, 16, v126
	v_and_b32_e32 v137, 0xffff0000, v126
	v_lshlrev_b32_e32 v138, 16, v127
	v_and_b32_e32 v139, 0xffff0000, v127
	s_waitcnt lgkmcnt(7)
	v_mul_f32_e32 v172, v141, v133
	v_mul_f32_e32 v174, v141, v137
	v_fmac_f32_e32 v172, v140, v132
	v_fmac_f32_e32 v174, v140, v136
	v_mul_f32_e32 v173, v143, v135
	v_mul_f32_e32 v175, v143, v139
	v_fmac_f32_e32 v173, v142, v134
	v_fmac_f32_e32 v175, v142, v138
	ds_read_b128 v[140:143], v3 offset:6144
	v_add_f32_e32 v172, v172, v173
	v_add_f32_e32 v174, v174, v175
	v_add_f32_e32 v80, v80, v172
	v_add_f32_e32 v81, v81, v174
	s_waitcnt lgkmcnt(7)
; __device__ __forceinline__ void logf_phase(const Args& a, int l, const u64* ssv, LAS unsigned char* lds, int gw, int NGW, int wave, int lane) {
;     ...
;         for (int j = 0; j < 8; ++j) { float s0 = 0.f, s1 = 0.f;
; #pragma unroll
;             for (int i = 0; i < 8; ++i) { const f32x4 w = wl[j * (DM / 4) + lane + 64 * i];
;                 s0 += (h0[i][0] * w[0] + h0[i][1] * w[1]) + (h0[i][2] * w[2] + h0[i][3] * w[3]);
;                 s1 += (h1[i][0] * w[0] + h1[i][1] * w[1]) + (h1[i][2] * w[2] + h1[i][3] * w[3]); }
;             sa[j] = s0; sb[j] = s1;
;             __builtin_amdgcn_sched_barrier(0); }
	v_mul_f32_e32 v172, v145, v133
	v_mul_f32_e32 v174, v145, v137
	v_fmac_f32_e32 v172, v144, v132
	v_fmac_f32_e32 v174, v144, v136
	v_mul_f32_e32 v173, v147, v135
	v_mul_f32_e32 v175, v147, v139
	v_fmac_f32_e32 v173, v146, v134
	v_fmac_f32_e32 v175, v146, v138
	ds_read_b128 v[144:147], v3 offset:14336
	v_add_f32_e32 v172, v172, v173
	v_add_f32_e32 v174, v174, v175
	v_add_f32_e32 v82, v82, v172
	v_add_f32_e32 v83, v83, v174
	s_waitcnt lgkmcnt(7)
	v_mul_f32_e32 v172, v149, v133
	v_mul_f32_e32 v174, v149, v137
	v_fmac_f32_e32 v172, v148, v132
	v_fmac_f32_e32 v174, v148, v136
	v_mul_f32_e32 v173, v151, v135
	v_mul_f32_e32 v175, v151, v139
	v_fmac_f32_e32 v173, v150, v134
	v_fmac_f32_e32 v175, v150, v138
	ds_read_b128 v[148:151], v3 offset:22528
	v_add_f32_e32 v172, v172, v173
	v_add_f32_e32 v174, v174, v175
	v_add_f32_e32 v84, v84, v172
	v_add_f32_e32 v85, v85, v174
	s_waitcnt lgkmcnt(7)
	v_mul_f32_e32 v172, v153, v133
	v_mul_f32_e32 v174, v153, v137
	v_fmac_f32_e32 v172, v152, v132
	v_fmac_f32_e32 v174, v152, v136
	v_mul_f32_e32 v173, v155, v135
	v_mul_f32_e32 v175, v155, v139
	v_fmac_f32_e32 v173, v154, v134
	v_fmac_f32_e32 v175, v154, v138
	ds_read_b128 v[152:155], v3 offset:30720
	v_add_f32_e32 v172, v172, v173
	v_add_f32_e32 v174, v174, v175
	v_add_f32_e32 v86, v86, v172
	v_add_f32_e32 v87, v87, v174
	s_waitcnt lgkmcnt(7)
	v_mul_f32_e32 v172, v157, v133
	v_mul_f32_e32 v174, v157, v137
	v_fmac_f32_e32 v172, v156, v132
	v_fmac_f32_e32 v174, v156, v136
	v_mul_f32_e32 v173, v159, v135
	v_mul_f32_e32 v175, v159, v139
	v_fmac_f32_e32 v173, v158, v134
	v_fmac_f32_e32 v175, v158, v138
	ds_read_b128 v[156:159], v3 offset:38912
	v_add_f32_e32 v172, v172, v173
	v_add_f32_e32 v174, v174, v175
	v_add_f32_e32 v88, v88, v172
	v_add_f32_e32 v89, v89, v174
	s_waitcnt lgkmcnt(7)
	v_mul_f32_e32 v172, v161, v133
	v_mul_f32_e32 v174, v161, v137
	v_fmac_f32_e32 v172, v160, v132
	v_fmac_f32_e32 v174, v160, v136
	v_mul_f32_e32 v173, v163, v135
	v_mul_f32_e32 v175, v163, v139
	v_fmac_f32_e32 v173, v162, v134
	v_fmac_f32_e32 v175, v162, v138
	ds_read_b128 v[160:163], v3 offset:47104
	v_add_f32_e32 v172, v172, v173
	v_add_f32_e32 v174, v174, v175
	v_add_f32_e32 v90, v90, v172
	v_add_f32_e32 v91, v91, v174
	s_waitcnt lgkmcnt(7)
	v_mul_f32_e32 v172, v165, v133
	v_mul_f32_e32 v174, v165, v137
	v_fmac_f32_e32 v172, v164, v132
	v_fmac_f32_e32 v174, v164, v136
	v_mul_f32_e32 v173, v167, v135
	v_mul_f32_e32 v175, v167, v139
	v_fmac_f32_e32 v173, v166, v134
	v_fmac_f32_e32 v175, v166, v138
	ds_read_b128 v[164:167], v3 offset:55296
	v_add_f32_e32 v172, v172, v173
	v_add_f32_e32 v174, v174, v175
	v_add_f32_e32 v92, v92, v172
	v_add_f32_e32 v93, v93, v174
	s_waitcnt lgkmcnt(7)
	v_mul_f32_e32 v172, v169, v133
	v_mul_f32_e32 v174, v169, v137
	v_fmac_f32_e32 v172, v168, v132
	v_fmac_f32_e32 v174, v168, v136
	v_mul_f32_e32 v173, v171, v135
	v_mul_f32_e32 v175, v171, v139
	v_fmac_f32_e32 v173, v170, v134
	v_fmac_f32_e32 v175, v170, v138
	ds_read_b128 v[168:171], v3 offset:63488
	v_add_f32_e32 v172, v172, v173
	v_add_f32_e32 v174, v174, v175
	v_add_f32_e32 v19, v19, v172
	v_add_f32_e32 v0, v0, v174
	s_waitcnt vmcnt(2)
	v_lshlrev_b32_e32 v132, 16, v112
	v_and_b32_e32 v133, 0xffff0000, v112
	v_lshlrev_b32_e32 v134, 16, v113
	v_and_b32_e32 v135, 0xffff0000, v113
	v_lshlrev_b32_e32 v136, 16, v128
	v_and_b32_e32 v137, 0xffff0000, v128
	v_lshlrev_b32_e32 v138, 16, v129
	v_and_b32_e32 v139, 0xffff0000, v129
	s_waitcnt lgkmcnt(7)
	v_mul_f32_e32 v172, v141, v133
	v_mul_f32_e32 v174, v141, v137
	v_fmac_f32_e32 v172, v140, v132
	v_fmac_f32_e32 v174, v140, v136
	v_mul_f32_e32 v173, v143, v135
	v_mul_f32_e32 v175, v143, v139
	v_fmac_f32_e32 v173, v142, v134
	v_fmac_f32_e32 v175, v142, v138
	ds_read_b128 v[140:143], v3 offset:7168
	v_add_f32_e32 v172, v172, v173
	v_add_f32_e32 v174, v174, v175
	v_add_f32_e32 v80, v80, v172
	v_add_f32_e32 v81, v81, v174
	s_waitcnt lgkmcnt(7)
	v_mul_f32_e32 v172, v145, v133
	v_mul_f32_e32 v174, v145, v137
	v_fmac_f32_e32 v172, v144, v132
	v_fmac_f32_e32 v174, v144, v136
	v_mul_f32_e32 v173, v147, v135
	v_mul_f32_e32 v175, v147, v139
	v_fmac_f32_e32 v173, v146, v134
	v_fmac_f32_e32 v175, v146, v138
	ds_read_b128 v[144:147], v3 offset:15360
	v_add_f32_e32 v172, v172, v173
	v_add_f32_e32 v174, v174, v175
	v_add_f32_e32 v82, v82, v172
	v_add_f32_e32 v83, v83, v174
	s_waitcnt lgkmcnt(7)
	v_mul_f32_e32 v172, v149, v133
	v_mul_f32_e32 v174, v149, v137
	v_fmac_f32_e32 v172, v148, v132
	v_fmac_f32_e32 v174, v148, v136
	v_mul_f32_e32 v173, v151, v135
	v_mul_f32_e32 v175, v151, v139
	v_fmac_f32_e32 v173, v150, v134
	v_fmac_f32_e32 v175, v150, v138
	ds_read_b128 v[148:151], v3 offset:23552
	v_add_f32_e32 v172, v172, v173
	v_add_f32_e32 v174, v174, v175
	v_add_f32_e32 v84, v84, v172
	v_add_f32_e32 v85, v85, v174
	s_waitcnt lgkmcnt(7)
	v_mul_f32_e32 v172, v153, v133
	v_mul_f32_e32 v174, v153, v137
	v_fmac_f32_e32 v172, v152, v132
	v_fmac_f32_e32 v174, v152, v136
	v_mul_f32_e32 v173, v155, v135
	v_mul_f32_e32 v175, v155, v139
	v_fmac_f32_e32 v173, v154, v134
	v_fmac_f32_e32 v175, v154, v138
	ds_read_b128 v[152:155], v3 offset:31744
	v_add_f32_e32 v172, v172, v173
	v_add_f32_e32 v174, v174, v175
	v_add_f32_e32 v86, v86, v172
	v_add_f32_e32 v87, v87, v174
	s_waitcnt lgkmcnt(7)
	v_mul_f32_e32 v172, v157, v133
	v_mul_f32_e32 v174, v157, v137
	v_fmac_f32_e32 v172, v156, v132
	v_fmac_f32_e32 v174, v156, v136
	v_mul_f32_e32 v173, v159, v135
	v_mul_f32_e32 v175, v159, v139
	v_fmac_f32_e32 v173, v158, v134
	v_fmac_f32_e32 v175, v158, v138
	ds_read_b128 v[156:159], v3 offset:39936
	v_add_f32_e32 v172, v172, v173
	v_add_f32_e32 v174, v174, v175
	v_add_f32_e32 v88, v88, v172
	v_add_f32_e32 v89, v89, v174
	s_waitcnt lgkmcnt(7)
; __device__ __forceinline__ void logf_phase(const Args& a, int l, const u64* ssv, LAS unsigned char* lds, int gw, int NGW, int wave, int lane) {
;     ...
;         for (int j = 0; j < 8; ++j) { float s0 = 0.f, s1 = 0.f;
; #pragma unroll
;             for (int i = 0; i < 8; ++i) { const f32x4 w = wl[j * (DM / 4) + lane + 64 * i];
;                 s0 += (h0[i][0] * w[0] + h0[i][1] * w[1]) + (h0[i][2] * w[2] + h0[i][3] * w[3]);
;                 s1 += (h1[i][0] * w[0] + h1[i][1] * w[1]) + (h1[i][2] * w[2] + h1[i][3] * w[3]); }
;             sa[j] = s0; sb[j] = s1;
;             __builtin_amdgcn_sched_barrier(0); }
;         float f0, f1;
;         { const bool b0 = lane & 1, b1 = lane & 2, b2 = lane & 4;
;           float ta[4], tb[4];
; #pragma unroll
;           for (int k = 0; k < 4; ++k) { const float ka = b0 ? sa[2 * k + 1] : sa[2 * k], xa = b0 ? sa[2 * k] : sa[2 * k + 1]; ta[k] = ka + __shfl_xor(xa, 1);
;                                         const float kb = b0 ? sb[2 * k + 1] : sb[2 * k], xb = b0 ? sb[2 * k] : sb[2 * k + 1]; tb[k] = kb + __shfl_xor(xb, 1); }
;           float ua[2], ub[2];
; #pragma unroll
;           for (int k = 0; k < 2; ++k) { const float ka = b1 ? ta[2 * k + 1] : ta[2 * k], xa = b1 ? ta[2 * k] : ta[2 * k + 1]; ua[k] = ka + __shfl_xor(xa, 2);
;                                         const float kb = b1 ? tb[2 * k + 1] : tb[2 * k], xb = b1 ? tb[2 * k] : tb[2 * k + 1]; ub[k] = kb + __shfl_xor(xb, 2); }
;           { const float ka = b2 ? ua[1] : ua[0], xa = b2 ? ua[0] : ua[1]; f0 = ka + __shfl_xor(xa, 4);
;             const float kb = b2 ? ub[1] : ub[0], xb = b2 ? ub[0] : ub[1]; f1 = kb + __shfl_xor(xb, 4); }
;           f0 += __shfl_xor(f0, 8); f0 += __shfl_xor(f0, 16); f0 += __shfl_xor(f0, 32);
;           f1 += __shfl_xor(f1, 8); f1 += __shfl_xor(f1, 16); f1 += __shfl_xor(f1, 32); }
	v_mul_f32_e32 v172, v161, v133
	v_mul_f32_e32 v174, v161, v137
	v_fmac_f32_e32 v172, v160, v132
	v_fmac_f32_e32 v174, v160, v136
	v_mul_f32_e32 v173, v163, v135
	v_mul_f32_e32 v175, v163, v139
	v_fmac_f32_e32 v173, v162, v134
	v_fmac_f32_e32 v175, v162, v138
	ds_read_b128 v[160:163], v3 offset:48128
	v_add_f32_e32 v172, v172, v173
	v_add_f32_e32 v174, v174, v175
	v_add_f32_e32 v90, v90, v172
	v_add_f32_e32 v91, v91, v174
	s_waitcnt lgkmcnt(7)
	v_mul_f32_e32 v172, v165, v133
	v_mul_f32_e32 v174, v165, v137
	v_fmac_f32_e32 v172, v164, v132
	v_fmac_f32_e32 v174, v164, v136
	v_mul_f32_e32 v173, v167, v135
	v_mul_f32_e32 v175, v167, v139
	v_fmac_f32_e32 v173, v166, v134
	v_fmac_f32_e32 v175, v166, v138
	ds_read_b128 v[164:167], v3 offset:56320
	v_add_f32_e32 v172, v172, v173
	v_add_f32_e32 v174, v174, v175
	v_add_f32_e32 v92, v92, v172
	v_add_f32_e32 v93, v93, v174
	s_waitcnt lgkmcnt(7)
	v_mul_f32_e32 v172, v169, v133
	v_mul_f32_e32 v174, v169, v137
	v_fmac_f32_e32 v172, v168, v132
	v_fmac_f32_e32 v174, v168, v136
	v_mul_f32_e32 v173, v171, v135
	v_mul_f32_e32 v175, v171, v139
	v_fmac_f32_e32 v173, v170, v134
	v_fmac_f32_e32 v175, v170, v138
	ds_read_b128 v[168:171], v3 offset:64512
	v_add_f32_e32 v172, v172, v173
	v_add_f32_e32 v174, v174, v175
	v_add_f32_e32 v19, v19, v172
	v_add_f32_e32 v0, v0, v174
	s_waitcnt vmcnt(0)
	v_lshlrev_b32_e32 v132, 16, v114
	v_and_b32_e32 v133, 0xffff0000, v114
	v_lshlrev_b32_e32 v134, 16, v115
	v_and_b32_e32 v135, 0xffff0000, v115
	v_lshlrev_b32_e32 v136, 16, v130
	v_and_b32_e32 v137, 0xffff0000, v130
	v_lshlrev_b32_e32 v138, 16, v131
	v_and_b32_e32 v139, 0xffff0000, v131
	s_waitcnt lgkmcnt(7)
	v_mul_f32_e32 v172, v141, v133
	v_mul_f32_e32 v174, v141, v137
	v_fmac_f32_e32 v172, v140, v132
	v_fmac_f32_e32 v174, v140, v136
	v_mul_f32_e32 v173, v143, v135
	v_mul_f32_e32 v175, v143, v139
	v_fmac_f32_e32 v173, v142, v134
	v_fmac_f32_e32 v175, v142, v138
	v_add_f32_e32 v172, v172, v173
	v_add_f32_e32 v174, v174, v175
	v_add_f32_e32 v80, v80, v172
	v_add_f32_e32 v81, v81, v174
	s_waitcnt lgkmcnt(6)
	v_mul_f32_e32 v172, v145, v133
	v_mul_f32_e32 v174, v145, v137
	v_fmac_f32_e32 v172, v144, v132
	v_fmac_f32_e32 v174, v144, v136
	v_mul_f32_e32 v173, v147, v135
	v_mul_f32_e32 v175, v147, v139
	v_fmac_f32_e32 v173, v146, v134
	v_fmac_f32_e32 v175, v146, v138
	v_add_f32_e32 v172, v172, v173
	v_add_f32_e32 v174, v174, v175
	v_add_f32_e32 v82, v82, v172
	v_add_f32_e32 v83, v83, v174
	s_waitcnt lgkmcnt(5)
	v_mul_f32_e32 v172, v149, v133
	v_mul_f32_e32 v174, v149, v137
	v_fmac_f32_e32 v172, v148, v132
	v_fmac_f32_e32 v174, v148, v136
	v_mul_f32_e32 v173, v151, v135
	v_mul_f32_e32 v175, v151, v139
	v_fmac_f32_e32 v173, v150, v134
	v_fmac_f32_e32 v175, v150, v138
	v_add_f32_e32 v172, v172, v173
	v_add_f32_e32 v174, v174, v175
	v_add_f32_e32 v84, v84, v172
	v_add_f32_e32 v85, v85, v174
	s_waitcnt lgkmcnt(4)
	v_mul_f32_e32 v172, v153, v133
	v_mul_f32_e32 v174, v153, v137
	v_fmac_f32_e32 v172, v152, v132
	v_fmac_f32_e32 v174, v152, v136
	v_mul_f32_e32 v173, v155, v135
	v_mul_f32_e32 v175, v155, v139
	v_fmac_f32_e32 v173, v154, v134
	v_fmac_f32_e32 v175, v154, v138
	v_add_f32_e32 v172, v172, v173
	v_add_f32_e32 v174, v174, v175
	v_add_f32_e32 v86, v86, v172
	v_add_f32_e32 v87, v87, v174
	s_waitcnt lgkmcnt(3)
	v_mul_f32_e32 v172, v157, v133
	v_mul_f32_e32 v174, v157, v137
	v_fmac_f32_e32 v172, v156, v132
	v_fmac_f32_e32 v174, v156, v136
	v_mul_f32_e32 v173, v159, v135
	v_mul_f32_e32 v175, v159, v139
	v_fmac_f32_e32 v173, v158, v134
	v_fmac_f32_e32 v175, v158, v138
	v_add_f32_e32 v172, v172, v173
	v_add_f32_e32 v174, v174, v175
	v_add_f32_e32 v88, v88, v172
	v_add_f32_e32 v89, v89, v174
	s_waitcnt lgkmcnt(2)
	v_mul_f32_e32 v172, v161, v133
	v_mul_f32_e32 v174, v161, v137
	v_fmac_f32_e32 v172, v160, v132
	v_fmac_f32_e32 v174, v160, v136
	v_mul_f32_e32 v173, v163, v135
	v_mul_f32_e32 v175, v163, v139
	v_fmac_f32_e32 v173, v162, v134
	v_fmac_f32_e32 v175, v162, v138
	v_add_f32_e32 v172, v172, v173
	v_add_f32_e32 v174, v174, v175
	v_add_f32_e32 v90, v90, v172
	v_add_f32_e32 v91, v91, v174
	s_waitcnt lgkmcnt(1)
	v_mul_f32_e32 v172, v165, v133
	v_mul_f32_e32 v174, v165, v137
	v_fmac_f32_e32 v172, v164, v132
	v_fmac_f32_e32 v174, v164, v136
	v_mul_f32_e32 v173, v167, v135
	v_mul_f32_e32 v175, v167, v139
	v_fmac_f32_e32 v173, v166, v134
	v_fmac_f32_e32 v175, v166, v138
	v_add_f32_e32 v172, v172, v173
	v_add_f32_e32 v174, v174, v175
	v_add_f32_e32 v92, v92, v172
	v_add_f32_e32 v93, v93, v174
	s_waitcnt lgkmcnt(0)
	v_mul_f32_e32 v172, v169, v133
	v_mul_f32_e32 v174, v169, v137
	v_fmac_f32_e32 v172, v168, v132
	v_fmac_f32_e32 v174, v168, v136
	v_mul_f32_e32 v173, v171, v135
	v_mul_f32_e32 v175, v171, v139
	v_fmac_f32_e32 v173, v170, v134
	v_fmac_f32_e32 v175, v170, v138
	v_add_f32_e32 v172, v172, v173
	v_add_f32_e32 v174, v174, v175
	v_add_f32_e32 v19, v19, v172
	v_add_f32_e32 v0, v0, v174
	v_cndmask_b32_e64 v10, v80, v82, s[36:37]
	ds_bpermute_b32 v10, v13, v10
	v_cndmask_b32_e64 v11, v82, v80, s[36:37]
	v_cndmask_b32_e64 v20, v81, v83, s[36:37]
	ds_bpermute_b32 v20, v13, v20
	v_cndmask_b32_e64 v22, v85, v87, s[36:37]
	s_waitcnt lgkmcnt(1)
	v_add_f32_e32 v10, v11, v10
	v_cndmask_b32_e64 v11, v84, v86, s[36:37]
	ds_bpermute_b32 v11, v13, v11
	ds_bpermute_b32 v22, v13, v22
	v_cndmask_b32_e64 v23, v88, v90, s[36:37]
	ds_bpermute_b32 v23, v13, v23
	v_cndmask_b32_e64 v24, v89, v91, s[36:37]
	v_cndmask_b32_e64 v21, v83, v81, s[36:37]
	ds_bpermute_b32 v24, v13, v24
	v_cndmask_b32_e64 v25, v92, v19, s[36:37]
	s_waitcnt lgkmcnt(4)
	v_add_f32_e32 v20, v21, v20
	v_cndmask_b32_e64 v21, v86, v84, s[36:37]
	ds_bpermute_b32 v25, v13, v25
	s_waitcnt lgkmcnt(4)
; __device__ __forceinline__ float rstd_of(u64 ss) { return rsqrtf((float)ss * (1.0f / 4294967296.0f) * (1.0f / DM) + EPS); }
; __device__ __forceinline__ void logf_phase(const Args& a, int l, const u64* ssv, LAS unsigned char* lds, int gw, int NGW, int wave, int lane) {
;     ...
;         { const bool b0 = lane & 1, b1 = lane & 2, b2 = lane & 4;
;           float ta[4], tb[4];
; #pragma unroll
;           for (int k = 0; k < 4; ++k) { const float ka = b0 ? sa[2 * k + 1] : sa[2 * k], xa = b0 ? sa[2 * k] : sa[2 * k + 1]; ta[k] = ka + __shfl_xor(xa, 1);
;                                         const float kb = b0 ? sb[2 * k + 1] : sb[2 * k], xb = b0 ? sb[2 * k] : sb[2 * k + 1]; tb[k] = kb + __shfl_xor(xb, 1); }
;           float ua[2], ub[2];
; #pragma unroll
;           for (int k = 0; k < 2; ++k) { const float ka = b1 ? ta[2 * k + 1] : ta[2 * k], xa = b1 ? ta[2 * k] : ta[2 * k + 1]; ua[k] = ka + __shfl_xor(xa, 2);
;                                         const float kb = b1 ? tb[2 * k + 1] : tb[2 * k], xb = b1 ? tb[2 * k] : tb[2 * k + 1]; ub[k] = kb + __shfl_xor(xb, 2); }
;           { const float ka = b2 ? ua[1] : ua[0], xa = b2 ? ua[0] : ua[1]; f0 = ka + __shfl_xor(xa, 4);
;             const float kb = b2 ? ub[1] : ub[0], xb = b2 ? ub[0] : ub[1]; f1 = kb + __shfl_xor(xb, 4); }
;           f0 += __shfl_xor(f0, 8); f0 += __shfl_xor(f0, 16); f0 += __shfl_xor(f0, 32);
;           f1 += __shfl_xor(f1, 8); f1 += __shfl_xor(f1, 16); f1 += __shfl_xor(f1, 32); }
;         const int r = (lane & 8) ? r1 : r0; const float fsel = (lane & 8) ? f1 : f0;
;         const float xv = fsel * rstd_of(ssv[r]) + a.b_forget[l * 8 + (lane & 7)];
;         const float lf = fminf(xv, 0.f) - log1pf(expf(-fabsf(xv)));
;         if (lane < 16) {
	v_add_f32_e32 v11, v21, v11
	v_cndmask_b32_e64 v21, v87, v85, s[36:37]
	s_waitcnt lgkmcnt(3)
	v_add_f32_e32 v21, v21, v22
	v_cndmask_b32_e64 v22, v90, v88, s[36:37]
	s_waitcnt lgkmcnt(2)
	v_add_f32_e32 v22, v22, v23
	v_cndmask_b32_e64 v23, v91, v89, s[36:37]
	s_waitcnt lgkmcnt(1)
	v_add_f32_e32 v23, v23, v24
	v_cndmask_b32_e64 v19, v19, v92, s[36:37]
	v_cndmask_b32_e64 v24, v93, v0, s[36:37]
	ds_bpermute_b32 v24, v13, v24
	s_waitcnt lgkmcnt(1)
	v_add_f32_e32 v19, v19, v25
	v_cndmask_b32_e64 v25, v10, v11, s[38:39]
	v_cndmask_b32_e64 v10, v11, v10, s[38:39]
	v_cndmask_b32_e64 v11, v20, v21, s[38:39]
	ds_bpermute_b32 v11, v14, v11
	v_cndmask_b32_e64 v0, v0, v93, s[36:37]
	s_waitcnt lgkmcnt(1)
	v_add_f32_e32 v0, v0, v24
	v_cndmask_b32_e64 v20, v21, v20, s[38:39]
	v_cndmask_b32_e64 v21, v22, v19, s[38:39]
	s_waitcnt lgkmcnt(0)
	v_add_f32_e32 v11, v20, v11
	v_cndmask_b32_e64 v20, v23, v0, s[38:39]
	ds_bpermute_b32 v25, v14, v25
	ds_bpermute_b32 v21, v14, v21
	ds_bpermute_b32 v20, v14, v20
	v_cndmask_b32_e64 v19, v19, v22, s[38:39]
	v_cndmask_b32_e64 v0, v0, v23, s[38:39]
	s_waitcnt lgkmcnt(2)
	v_add_f32_e32 v10, v10, v25
	s_waitcnt lgkmcnt(1)
	v_add_f32_e32 v19, v19, v21
	s_waitcnt lgkmcnt(0)
	v_add_f32_e32 v0, v0, v20
	v_cndmask_b32_e64 v21, v10, v19, s[40:41]
	v_cndmask_b32_e64 v20, v11, v0, s[40:41]
	ds_bpermute_b32 v21, v15, v21
	ds_bpermute_b32 v20, v15, v20
	v_cndmask_b32_e64 v10, v19, v10, s[40:41]
	v_cndmask_b32_e64 v0, v0, v11, s[40:41]
	s_waitcnt lgkmcnt(1)
	v_add_f32_e32 v10, v10, v21
	s_waitcnt lgkmcnt(0)
	v_add_f32_e32 v0, v0, v20
	ds_bpermute_b32 v11, v16, v10
	ds_bpermute_b32 v19, v16, v0
	s_waitcnt lgkmcnt(1)
	v_add_f32_e32 v10, v10, v11
	s_waitcnt lgkmcnt(0)
	v_add_f32_e32 v19, v0, v19
	ds_bpermute_b32 v11, v17, v10
	ds_bpermute_b32 v20, v17, v19
	s_waitcnt lgkmcnt(1)
	v_add_f32_e32 v0, v10, v11
	s_waitcnt lgkmcnt(0)
	v_add_f32_e32 v11, v19, v20
	ds_bpermute_b32 v10, v18, v0
	ds_bpermute_b32 v19, v18, v11
	s_and_saveexec_b64 s[16:17], s[44:45]
	s_cbranch_execz .LBB0_336
; __device__ __forceinline__ float rstd_of(u64 ss) { return rsqrtf((float)ss * (1.0f / 4294967296.0f) * (1.0f / DM) + EPS); }
; __device__ __forceinline__ void logf_phase(const Args& a, int l, const u64* ssv, LAS unsigned char* lds, int gw, int NGW, int wave, int lane) {
;     ...
;         const int r = (lane & 8) ? r1 : r0; const float fsel = (lane & 8) ? f1 : f0;
;         const float xv = fsel * rstd_of(ssv[r]) + a.b_forget[l * 8 + (lane & 7)];
;         const float lf = fminf(xv, 0.f) - log1pf(expf(-fabsf(xv)));
;         if (lane < 16) {
;             if (r < MX) { const int b = r >> 12, sq = r & 4095; logf[((size_t)b * 8 + (lane & 7)) * LKV + NMETA + sq] = lf; }
;             else { for (int bb = 0; bb < NB; ++bb) logf[((size_t)bb * 8 + (lane & 7)) * LKV + (r - MX)] = lf; }
	s_add_i32 s1, s0, 1
	s_waitcnt lgkmcnt(1)
	v_add_f32_e32 v0, v0, v10
	s_waitcnt lgkmcnt(0)
	v_add_f32_e32 v11, v11, v19
	v_mov_b32_e32 v10, s1
	v_mov_b32_e32 v19, s0
	v_cndmask_b32_e64 v10, v10, v19, s[42:43]
	v_cndmask_b32_e64 v0, v11, v0, s[42:43]
	v_ashrrev_i32_e32 v11, 31, v10
	v_lshl_add_u64 v[20:21], v[10:11], 3, s[4:5]
	v_mov_b32_e32 v20, v176
	v_mov_b32_e32 v21, v177
	s_mov_b32 s1, 0xbfb8aa3b
	s_waitcnt vmcnt(0)
	v_ffbh_u32_e32 v11, v21
	v_min_u32_e32 v11, 32, v11
	v_lshlrev_b64 v[20:21], v11, v[20:21]
	v_min_u32_e32 v19, 1, v20
	v_or_b32_e32 v19, v21, v19
	v_cvt_f32_u32_e32 v19, v19
	v_sub_u32_e32 v11, 32, v11
	v_ldexp_f32 v11, v19, v11
	v_mul_f32_e32 v11, 0x2f800000, v11
	v_fmamk_f32 v11, v11, 0x3a000000, v238
	v_cmp_gt_f32_e32 vcc, s34, v11
	v_mul_f32_e32 v19, 0x4b800000, v11
	s_nop 0
	v_cndmask_b32_e32 v11, v11, v19, vcc
	v_rsq_f32_e32 v11, v11
	s_nop 0
	v_mul_f32_e32 v19, 0x45800000, v11
	v_cndmask_b32_e32 v11, v11, v19, vcc
	v_mov_b32_e32 v19, v178
	s_waitcnt vmcnt(0)
	v_fmac_f32_e32 v19, v0, v11
	v_mul_f32_e64 v11, |v19|, s1
	v_fma_f32 v20, |v19|, s1, -v11
	s_mov_b32 s1, 0xb2a5705f
	v_rndne_f32_e32 v21, v11
	v_fma_f32 v20, |v19|, s1, v20
	v_sub_f32_e32 v11, v11, v21
	v_add_f32_e32 v11, v11, v20
	v_exp_f32_e32 v11, v11
	v_cvt_i32_f32_e32 v20, v21
	s_mov_b32 s1, 0x42ce8ed0
	v_cmp_ngt_f32_e64 vcc, |v19|, s1
	s_mov_b32 s1, 0xc2b17218
	v_ldexp_f32 v11, v11, v20
	v_cndmask_b32_e32 v11, 0, v11, vcc
	v_cmp_nlt_f32_e64 vcc, |v19|, s1
	v_min_f32_e32 v0, 0, v19
	s_mov_b32 s1, 0x3f2aaaab
	v_cndmask_b32_e32 v11, v228, v11, vcc
	v_add_f32_e32 v19, 1.0, v11
	v_add_f32_e32 v20, -1.0, v19
	v_sub_f32_e32 v21, v20, v19
	v_add_f32_e32 v21, 1.0, v21
	v_sub_f32_e32 v20, v11, v20
	v_add_f32_e32 v22, v20, v21
	v_frexp_mant_f32_e32 v20, v19
	v_cmp_gt_f32_e32 vcc, s1, v20
	v_cvt_f64_f32_e32 v[20:21], v19
	v_frexp_exp_i32_f64_e32 v20, v[20:21]
	v_subbrev_co_u32_e32 v20, vcc, 0, v20, vcc
	v_sub_u32_e32 v21, 0, v20
	v_ldexp_f32 v19, v19, v21
	v_ldexp_f32 v21, v22, v21
	v_add_f32_e32 v22, -1.0, v19
	v_add_f32_e32 v23, 1.0, v22
	v_sub_f32_e32 v23, v19, v23
	v_add_f32_e32 v23, v21, v23
	v_add_f32_e32 v24, v22, v23
	v_sub_f32_e32 v22, v22, v24
	v_add_f32_e32 v22, v23, v22
	v_add_f32_e32 v23, 1.0, v19
	v_add_f32_e32 v25, -1.0, v23
	v_sub_f32_e32 v19, v19, v25
	v_add_f32_e32 v19, v21, v19
	v_add_f32_e32 v21, v23, v19
	v_sub_f32_e32 v23, v23, v21
	v_add_f32_e32 v19, v19, v23
	v_rcp_f32_e32 v23, v21
	v_cvt_f32_i32_e32 v20, v20
	s_mov_b32 s1, 0x3f317218
	v_mul_f32_e32 v25, v24, v23
	v_mul_f32_e32 v26, v21, v25
	v_fma_f32 v27, v25, v21, -v26
	v_fmac_f32_e32 v27, v25, v19
	v_add_f32_e32 v28, v26, v27
	v_sub_f32_e32 v29, v24, v28
	v_sub_f32_e32 v24, v24, v29
	v_sub_f32_e32 v26, v28, v26
	v_sub_f32_e32 v24, v24, v28
	v_add_f32_e32 v22, v22, v24
	v_sub_f32_e32 v24, v26, v27
	v_add_f32_e32 v22, v24, v22
	v_add_f32_e32 v24, v29, v22
	v_mul_f32_e32 v26, v23, v24
	v_mul_f32_e32 v27, v21, v26
	v_fma_f32 v21, v26, v21, -v27
	v_fmac_f32_e32 v21, v26, v19
	v_sub_f32_e32 v19, v29, v24
	v_add_f32_e32 v19, v22, v19
	v_add_f32_e32 v22, v27, v21
	v_sub_f32_e32 v28, v24, v22
	v_sub_f32_e32 v24, v24, v28
	v_sub_f32_e32 v27, v22, v27
	v_sub_f32_e32 v22, v24, v22
	v_add_f32_e32 v19, v19, v22
	v_sub_f32_e32 v21, v27, v21
	v_add_f32_e32 v19, v21, v19
	v_add_f32_e32 v21, v25, v26
	v_add_f32_e32 v19, v28, v19
	v_sub_f32_e32 v22, v21, v25
	v_mul_f32_e32 v19, v23, v19
	v_sub_f32_e32 v22, v26, v22
	v_add_f32_e32 v19, v22, v19
	v_mul_f32_e32 v25, 0x3f317218, v20
	v_add_f32_e32 v22, v21, v19
	v_fma_f32 v26, v20, s1, -v25
	v_mul_f32_e32 v23, v22, v22
	v_mov_b32_e32 v24, 0x3ecc95a3
	v_fmac_f32_e32 v26, 0xb102e308, v20
	v_sub_f32_e32 v20, v22, v21
	v_fmamk_f32 v24, v23, 0x3e9b6dac, v24
	v_sub_f32_e32 v19, v19, v20
	v_add_f32_e32 v20, v25, v26
	v_fmaak_f32 v24, v23, v24, 0x3f2aaada
	v_sub_f32_e32 v21, v20, v25
	v_ldexp_f32 v25, v22, 1
	v_mul_f32_e32 v22, v22, v23
	v_mul_f32_e32 v22, v22, v24
	v_add_f32_e32 v23, v25, v22
	v_sub_f32_e32 v24, v23, v25
	v_ldexp_f32 v19, v19, 1
	v_sub_f32_e32 v22, v22, v24
	v_add_f32_e32 v19, v19, v22
	v_add_f32_e32 v22, v23, v19
	v_sub_f32_e32 v23, v22, v23
	v_sub_f32_e32 v19, v19, v23
	v_add_f32_e32 v23, v20, v22
	v_sub_f32_e32 v24, v23, v20
	v_sub_f32_e32 v25, v23, v24
	v_sub_f32_e32 v21, v26, v21
	v_sub_f32_e32 v20, v20, v25
	v_sub_f32_e32 v22, v22, v24
	v_add_f32_e32 v20, v22, v20
	v_add_f32_e32 v22, v21, v19
	v_sub_f32_e32 v24, v22, v21
	v_sub_f32_e32 v25, v22, v24
	v_sub_f32_e32 v21, v21, v25
	v_sub_f32_e32 v19, v19, v24
	v_add_f32_e32 v20, v22, v20
	v_add_f32_e32 v19, v19, v21
	v_add_f32_e32 v21, v23, v20
	v_sub_f32_e32 v22, v21, v23
	v_sub_f32_e32 v20, v20, v22
	v_add_f32_e32 v19, v19, v20
	s_mov_b32 s1, 0x7f800000
	v_add_f32_e32 v19, v21, v19
	v_cmp_neq_f32_e32 vcc, s1, v11
	s_mov_b32 s1, 0x33800000
	s_nop 0
	v_cndmask_b32_e32 v19, v228, v19, vcc
	v_cmp_lt_f32_e64 vcc, |v11|, s1
	s_movk_i32 s1, 0x3fff
	s_nop 0
	v_cndmask_b32_e32 v11, v19, v11, vcc
	v_sub_f32_e32 v19, v0, v11
	v_cmp_lt_i32_e32 vcc, s1, v10
	s_and_saveexec_b64 s[6:7], vcc
	s_xor_b64 s[18:19], exec, s[6:7]
	s_cbranch_execz .LBB0_340
	v_mov_b32_e32 v11, v1
	v_lshl_add_u64 v[10:11], v[10:11], 2, v[6:7]
	v_add_co_u32_e32 v20, vcc, 0xffff0000, v10
	s_nop 1
	v_addc_co_u32_e32 v21, vcc, -1, v11, vcc
	global_store_dword v[20:21], v19, off
	v_add_co_u32_e32 v20, vcc, 0x10000, v10
	s_nop 1
	v_addc_co_u32_e32 v21, vcc, 0, v11, vcc
	global_store_dword v[20:21], v19, off offset:2048
	v_add_co_u32_e32 v20, vcc, 0x31000, v10
	s_nop 1
	v_addc_co_u32_e32 v21, vcc, 0, v11, vcc
	v_add_co_u32_e32 v10, vcc, 0x51000, v10
	global_store_dword v[20:21], v19, off
	s_nop 0
	v_addc_co_u32_e32 v11, vcc, 0, v11, vcc
	global_store_dword v[10:11], v19, off offset:2048
